# v12 + P4: odd piece-owning workgroups run their split-K piece before their full tile (de-synchronises the HBM-bound full-tile epilogues)
# speedup vs baseline: 1.0021x; 1.0021x over previous
; __device__ __forceinline__ int relaunder(Frame& F) { int t2 = threadIdx.x; asm volatile("" : "+v"(t2)); F.tid = t2; GAS unsigned char* w = F.ws; asm volatile("" : "+s"(w)); F.ws = w; GAS float* o = F.out; asm volatile("" : "+s"(o)); F.out = o; return 0; }
;     __host__ __device__ __forceinline__ bool next(int i, Unit& u) const {
;         const int L = i * G + c;
;         int pm, pn, kp; bool ok = true;
;         if (L < nfull) {
;             int wgid = L; { const int q = nfull / NXCD, xcd = wgid % NXCD, off = wgid / NXCD; wgid = xcd * q + off; }
;             const int nig = WGM * nN, gid = wgid / nig, fm = gid * WGM;
;             pm = fm + ((wgid % nig) % WGM); pn = (wgid % nig) / WGM; kp = -1;
;         } else {
;             const int j = L - nfull; ok = j < 2 * nN * np;
;             const int t = j / np; kp = j - t * np; pm = MP / BM + t / nN; pn = t % nN;
;         }
;         u.pm = pm; u.pn = pn; u.kp = kp; return ok;
; __global__ void __launch_bounds__(NWAVES * 64, 2) mk_fwd(Args args) {
;     ...
;     if (IN(4)) for (int rep_ = relaunder(F); rep_ < NREP(4); ++rep_) {
;         pg8::Gemm g{WSP(bf16, WS_ACT), WSP(bf16, WS_W1D), DFF, DFF, DFF, 0, KP_DOWN, WSC_DOWN}; pg8::SplitOrder S; S.init(DM, DFF / KP_DOWN, F.G, (int)blockIdx.x);
;         pg8::EpiResid<false> E{INP(0), WSP(bf16, WS_X), WSP(float, WS_MODS) + 2 * DM, 0.5f};
;         pg8::gemm_phase8<decltype(E), pg8::SplitOrder, true>(F.lds, g, S, E);
.LBB0_483:
	s_cmp_lt_i32 s84, 5
	s_cselect_b64 s[0:1], -1, 0
	s_cmp_gt_i32 s85, 4
	s_cselect_b64 s[2:3], -1, 0
	s_and_b64 s[0:1], s[0:1], s[2:3]
	s_andn2_b64 vcc, exec, s[0:1]
	s_cbranch_vccnz .LBB0_660
	v_mov_b32_e32 v1, v0
	s_and_b32 s101, s97, 1
	s_lshl_b32 s101, s101, 8
	s_cmp_lt_u32 s97, 0xb0
	s_cselect_b32 s101, s101, 0
	s_add_i32 s97, s97, s101
	s_cmpk_lt_i32 s97, 0x100
	v_writelane_b32 v253, s64, 42
	v_readfirstlane_b32 s2, v0
	s_nop 0
	v_writelane_b32 v253, s65, 43
	v_writelane_b32 v253, s66, 44
	v_writelane_b32 v253, s67, 45
	v_writelane_b32 v253, s68, 46
	v_writelane_b32 v253, s69, 47
	v_writelane_b32 v253, s70, 48
	v_writelane_b32 v253, s71, 49
	v_writelane_b32 v253, s72, 50
	v_writelane_b32 v253, s73, 51
	v_writelane_b32 v253, s74, 52
	v_writelane_b32 v253, s75, 53
	v_writelane_b32 v253, s76, 54
	v_writelane_b32 v253, s77, 55
	v_writelane_b32 v253, s78, 56
	v_writelane_b32 v253, s79, 57
	s_cbranch_scc1 .LBB0_486
	s_add_i32 s0, s97, 0xffffff00
	s_mul_hi_u32 s1, s0, 0xba2e8ba3
	s_lshr_b32 s3, s1, 3
	s_bfe_u32 s80, s1, 0x30003
	s_lshr_b32 s1, s1, 6
	s_add_i32 s75, s1, 32
	s_mul_i32 s1, s3, -11
	s_add_i32 s24, s1, s0
	s_cmpk_lt_u32 s0, 0xb0
	s_cselect_b64 s[0:1], -1, 0
	s_branch .LBB0_487

; #define PG8_WAIT_V(n) asm volatile("s_waitcnt vmcnt(" #n ")" ::: "memory")
; #define PG8_BAR __builtin_amdgcn_s_barrier()
; #define PG8_WAIT_V(n) asm volatile("s_waitcnt vmcnt(" #n ")" ::: "memory")
; template <class Epi, class Sched, bool ALIGN_EPI = false>
; __device__ __forceinline__ void gemm_phase8(PG8_LAS unsigned char* lds, const Gemm g, const Sched& S, const Epi& E) {
;     const int tid = threadIdx.x, wid = __builtin_amdgcn_readfirstlane(tid >> 6), lane = tid & 63, wr = wid >> 2, wc = wid & 3, fr = lane & 15, fq = lane >> 4;
;     unsigned voffA[2], voffB[2];
; #pragma unroll
;     for (int i = 0; i < 2; ++i) { int R, C; stage_rc8(tid * 16 + i * 8192, R, C); const int Rb = Epi::PERM ? ((R & ~31) + perm32(R & 31)) : R;
;         voffA[i] = (unsigned)(R * g.lda + C); voffB[i] = (unsigned)(Rb * g.ldb + C); }
;     const size_t kstep = (size_t)128;
;     const size_t hstepA = (size_t)HALF * g.lda, hstepB = (size_t)HALF * g.ldb;
;     const size_t tstepA = 2 * hstepA, tstepB = 2 * hstepB;
;     const size_t astep = (size_t)g.acol;
;     const unsigned ldsw = (unsigned)wid * 1024u;
;     const int aoff = lds_byte8(wr * 64 + fr, fq * 32), boff = lds_byte8(wc * 32 + fr, fq * 32);
;     ...
;     Unit cur, nxt; int ui = 0;
;     if (!S.next(0, cur)) return;
;     f32x4 acc[2][2][4][2];
; #pragma unroll
;     for (int a = 0; a < 2; ++a)
; #pragma unroll
;         for (int b = 0; b < 2; ++b)
; #pragma unroll
;             for (int m = 0; m < 4; ++m)
; #pragma unroll
;                 for (int n = 0; n < 2; ++n) acc[a][b][m][n] = (f32x4){0.f, 0.f, 0.f, 0.f};
;     v8i At[4], B0[2], B1[2];
;     int wsc = g.wscale, asc = 0x7f7f7f7f;
;     asm volatile("" : "+v"(wsc), "+v"(asc));
;     const char* cA = (const char*)g.A + (size_t)cur.pm * tstepA + (size_t)cur.pn * astep + (cur.kp > 0 ? (size_t)cur.kp * g.kpiece : 0); const char* cB = (const char*)g.Bt + (size_t)cur.pn * tstepB + (cur.kp > 0 ? (size_t)cur.kp * g.kpiece : 0);
;     S.a_ready(cur);
;     PG8_STAGE(PG8_SB(0, 0), cB, voffB); PG8_STAGE(PG8_SB(0, 1), cB + hstepB, voffB); PG8_STAGE(PG8_SA(0, 0), cA, voffA); PG8_STAGE(PG8_SA(0, 1), cA + hstepA, voffA);
;     if (wr == 1) PG8_BAR;
;     PG8_WAIT_V(2); PG8_BAR;
;     PG8_STAGE(PG8_SB(1, 0), cB + kstep, voffB); PG8_STAGE(PG8_SA(1, 0), cA + kstep, voffA); PG8_STAGE(PG8_SB(1, 1), cB + hstepB + kstep, voffB);
;     PG8_WAIT_V(6); PG8_BAR;
.LBB0_487:
	s_sub_i32 s97, s97, s101
	v_readlane_b32 s4, v253, 42
	v_readlane_b32 s18, v253, 56
	v_readlane_b32 s5, v253, 43
	v_readlane_b32 s19, v253, 57
	s_add_u32 s4, s18, 0x5800000
	s_addc_u32 s5, s19, 0
	s_andn2_b64 vcc, exec, s[0:1]
	v_readlane_b32 s6, v253, 44
	v_readlane_b32 s7, v253, 45
	v_readlane_b32 s8, v253, 46
	v_readlane_b32 s9, v253, 47
	v_readlane_b32 s10, v253, 48
	v_readlane_b32 s11, v253, 49
	v_readlane_b32 s12, v253, 50
	v_readlane_b32 s13, v253, 51
	v_readlane_b32 s14, v253, 52
	v_readlane_b32 s15, v253, 53
	v_readlane_b32 s16, v253, 54
	v_readlane_b32 s17, v253, 55
	s_cbranch_vccnz .LBB0_513
	s_waitcnt vmcnt(0)
	v_lshrrev_b32_e32 v12, 1, v0
	v_lshrrev_b32_e32 v4, 5, v0
	v_lshlrev_b32_e32 v1, 4, v0
	v_and_b32_e32 v3, 24, v12
	v_and_b32_e32 v4, 4, v4
	v_bfe_u32 v5, v0, 2, 2
	v_bfe_u32 v2, v0, 2, 4
	v_and_b32_e32 v1, 48, v1
	v_or3_b32 v3, v4, v5, v3
	v_lshrrev_b32_e32 v4, 3, v0
	v_and_b32_e32 v10, 64, v0
	v_bitop3_b32 v11, v12, v1, 16 bitop3:0x6c
	v_and_or_b32 v5, v4, 48, v2
	v_and_or_b32 v4, v4, 32, v3
	v_or_b32_e32 v1, v11, v10
	v_mul_u32_u24_e32 v4, 0x1600, v4
	v_readlane_b32 s8, v253, 42
	v_or_b32_e32 v164, v4, v1
	v_bfe_u32 v4, v0, 3, 25
	v_readlane_b32 s22, v253, 56
	v_or_b32_e32 v4, 64, v4
	s_movk_i32 s0, 0x70
	v_readlane_b32 s23, v253, 57
	s_add_u32 s33, s22, 0x11600000
	v_and_or_b32 v2, v4, s0, v2
	s_movk_i32 s0, 0x60
	s_mov_b32 s1, 0
	s_addc_u32 s52, s23, 0
	v_and_or_b32 v3, v4, s0, v3
	s_lshr_b32 s0, s2, 6
	s_mov_b32 s25, s1
	s_lshr_b32 s3, s2, 8
	s_lshl_b32 s53, s0, 10
	s_lshl_b64 s[6:7], s[24:25], 9
	v_readlane_b32 s11, v253, 45
	s_cmp_gt_i32 s24, 0
	v_readlane_b32 s10, v253, 44
	s_cselect_b32 s11, s6, 0
	s_mul_i32 s6, s80, 0x160000
	s_cselect_b32 s10, s7, 0
	s_ashr_i32 s7, s6, 31
	s_add_u32 s6, s4, s6
	s_addc_u32 s7, s5, s7
	s_add_u32 s30, s6, s11
	v_mul_u32_u24_e32 v13, 0x1600, v5
	v_mul_u32_u24_e32 v14, 0x1600, v2
	v_mul_u32_u24_e32 v2, 0x1600, v3
	s_addc_u32 s31, s7, s10
	s_add_i32 s54, s53, 0
	v_readlane_b32 s9, v253, 43
	v_or_b32_e32 v162, v13, v1
	v_or_b32_e32 v166, v14, v1
	v_or_b32_e32 v168, v2, v1
	v_mov_b32_e32 v1, 0x79797979
	v_mov_b32_e32 v182, 0x7f7f7f7f
	s_add_i32 m0, s54, 0x10000
	s_mul_i32 s9, s75, 0x160000
	global_load_lds_dwordx4 v164, s[30:31]
	s_add_i32 m0, s54, 0x12000
	s_mul_hi_i32 s8, s75, 0x160000
	s_add_u32 s9, s33, s9
	s_addc_u32 s8, s52, s8
	s_add_u32 s6, s30, 0xb0000
	global_load_lds_dwordx4 v168, s[30:31]
	s_addc_u32 s7, s31, 0
	s_add_i32 m0, s54, 0x14000
	v_mov_b32_e32 v165, 0
	global_load_lds_dwordx4 v164, s[6:7]
	s_add_i32 m0, s54, 0x16000
	s_add_u32 s28, s9, s11
	s_addc_u32 s29, s8, s10
	s_add_i32 s55, s54, 0x2000
	global_load_lds_dwordx4 v168, s[6:7]
	s_mov_b32 m0, s54
	s_add_u32 s6, s28, 0xb0000
	global_load_lds_dwordx4 v162, s[28:29]
	s_mov_b32 m0, s55
	s_addc_u32 s7, s29, 0
	s_add_i32 s56, s54, 0x4000
	global_load_lds_dwordx4 v166, s[28:29]
	s_mov_b32 m0, s56
	s_add_i32 s57, s54, 0x6000
	global_load_lds_dwordx4 v162, s[6:7]
	s_mov_b32 m0, s57
	v_mov_b32_e32 v169, v165
	global_load_lds_dwordx4 v166, s[6:7]
	v_mov_b32_e32 v163, v165
	v_mov_b32_e32 v167, v165
	s_cmp_eq_u32 s3, 1
	v_lshl_add_u64 v[8:9], s[30:31], 0, v[164:165]
	v_lshl_add_u64 v[6:7], s[30:31], 0, v[168:169]
	s_mov_b32 s58, 0x12000
	v_lshl_add_u64 v[4:5], s[28:29], 0, v[162:163]
	v_lshl_add_u64 v[2:3], s[28:29], 0, v[166:167]
	s_cselect_b64 s[6:7], -1, 0
	s_cmp_lg_u32 s3, 1
	s_movk_i32 s59, 0x2000
	v_readlane_b32 s12, v253, 46
	v_readlane_b32 s13, v253, 47
	v_readlane_b32 s14, v253, 48
	v_readlane_b32 s15, v253, 49
	v_readlane_b32 s16, v253, 50
	v_readlane_b32 s17, v253, 51
	v_readlane_b32 s18, v253, 52
	v_readlane_b32 s19, v253, 53
	v_readlane_b32 s20, v253, 54
	v_readlane_b32 s21, v253, 55
	s_cbranch_scc1 .LBB0_490
	s_barrier

;     __host__ __device__ __forceinline__ bool next(int i, Unit& u) const {
;         const int L = i * G + c;
;         int pm, pn, kp; bool ok = true;
;         if (L < nfull) {
;             int wgid = L; { const int q = nfull / NXCD, xcd = wgid % NXCD, off = wgid / NXCD; wgid = xcd * q + off; }
;             const int nig = WGM * nN, gid = wgid / nig, fm = gid * WGM;
;             pm = fm + ((wgid % nig) % WGM); pn = (wgid % nig) / WGM; kp = -1;
;         } else {
;             const int j = L - nfull; ok = j < 2 * nN * np;
;             const int t = j / np; kp = j - t * np; pm = MP / BM + t / nN; pn = t % nN;
;         }
; template <class Epi, class Sched, bool ALIGN_EPI = false>
; __device__ __forceinline__ void gemm_phase8(PG8_LAS unsigned char* lds, const Gemm g, const Sched& S, const Epi& E) {
;     ...
;         const bool has_next = S.next(ui + 1, nxt);
;         const size_t nko = (has_next && nxt.kp > 0) ? (size_t)nxt.kp * g.kpiece : 0;
;         const char* nA = has_next ? (const char*)g.A + (size_t)nxt.pm * tstepA + (size_t)nxt.pn * astep + nko : cA; const char* nB = has_next ? (const char*)g.Bt + (size_t)nxt.pn * tstepB + nko : cB;
.LBB0_493:
	s_add_i32 s72, s72, 1
	s_mul_i32 s22, s72, s94
	s_add_i32 s22, s22, s97
	s_cmp_eq_u32 s72, 1
	s_cselect_b32 s100, s101, 0
	s_sub_i32 s22, s22, s100
	s_cmpk_gt_i32 s22, 0xff
	s_mov_b64 s[2:3], -1
	s_cbranch_scc0 .LBB0_495
	s_add_i32 s0, s22, 0xffffff00
	s_cmpk_lt_u32 s0, 0xb0
	s_mul_hi_u32 s2, s0, 0xba2e8ba3
	s_cselect_b64 s[20:21], -1, 0
	s_lshr_b32 s3, s2, 3
	s_mul_i32 s3, s3, -11
	s_add_i32 s0, s3, s0
	s_lshr_b32 s3, s2, 6
	s_add_i32 s73, s3, 32
	s_bfe_u32 s74, s2, 0x30003
	s_mov_b64 s[2:3], 0
